# MLA uq/ukv epilogue stores (Q, QR, KALL, VALL) write-through (sc1) as well: less dirty L2 at the MLA in-proj->attention barriers
# speedup vs baseline: 1.0125x; 1.0018x over previous
.Lk2_body:
	s_nop 0
	v_pk_mul_f32 v[126:127], v[126:127], v[134:135] op_sel_hi:[1,0]
	v_pk_mul_f32 v[128:129], v[128:129], v[134:135] op_sel_hi:[1,0]
	v_pk_mul_f32 v[122:123], v[122:123], v[134:135] op_sel_hi:[1,0]
	v_pk_mul_f32 v[124:125], v[124:125], v[134:135] op_sel_hi:[1,0]
	v_pk_mul_f32 v[118:119], v[118:119], v[134:135] op_sel_hi:[1,0]
	v_pk_mul_f32 v[120:121], v[120:121], v[134:135] op_sel_hi:[1,0]
	v_pk_mul_f32 v[114:115], v[114:115], v[134:135] op_sel_hi:[1,0]
	v_pk_mul_f32 v[116:117], v[116:117], v[134:135] op_sel_hi:[1,0]
	v_cvt_pk_bf16_f32 v146, v126, v127
	v_cvt_pk_bf16_f32 v147, v128, v129
	v_cvt_pk_bf16_f32 v148, v122, v123
	v_cvt_pk_bf16_f32 v149, v124, v125
	global_store_dwordx4 v130, v[146:149], s[6:7] sc1
	v_cvt_pk_bf16_f32 v150, v118, v119
	v_cvt_pk_bf16_f32 v151, v120, v121
	v_cvt_pk_bf16_f32 v152, v114, v115
	v_cvt_pk_bf16_f32 v153, v116, v117
	global_store_dwordx4 v130, v[150:153], s[6:7] offset:256 sc1
	s_add_u32 s6, s6, s33
	s_addc_u32 s7, s7, 0
	v_pk_mul_f32 v[108:109], v[108:109], v[134:135] op_sel:[0,1] op_sel_hi:[1,1]
	v_pk_mul_f32 v[110:111], v[110:111], v[134:135] op_sel:[0,1] op_sel_hi:[1,1]
	v_pk_mul_f32 v[104:105], v[104:105], v[134:135] op_sel:[0,1] op_sel_hi:[1,1]
	v_pk_mul_f32 v[106:107], v[106:107], v[134:135] op_sel:[0,1] op_sel_hi:[1,1]
	v_pk_mul_f32 v[100:101], v[100:101], v[134:135] op_sel:[0,1] op_sel_hi:[1,1]
	v_pk_mul_f32 v[102:103], v[102:103], v[134:135] op_sel:[0,1] op_sel_hi:[1,1]
	v_pk_mul_f32 v[96:97], v[96:97], v[134:135] op_sel:[0,1] op_sel_hi:[1,1]
	v_pk_mul_f32 v[98:99], v[98:99], v[134:135] op_sel:[0,1] op_sel_hi:[1,1]
	v_cvt_pk_bf16_f32 v146, v108, v109
	v_cvt_pk_bf16_f32 v147, v110, v111
	v_cvt_pk_bf16_f32 v148, v104, v105
	v_cvt_pk_bf16_f32 v149, v106, v107
	global_store_dwordx4 v130, v[146:149], s[6:7] sc1
	v_cvt_pk_bf16_f32 v150, v100, v101
	v_cvt_pk_bf16_f32 v151, v102, v103
	v_cvt_pk_bf16_f32 v152, v96, v97
	v_cvt_pk_bf16_f32 v153, v98, v99
	global_store_dwordx4 v130, v[150:153], s[6:7] offset:256 sc1
	s_add_u32 s6, s6, s33
	s_addc_u32 s7, s7, 0
	v_pk_mul_f32 v[92:93], v[92:93], v[136:137] op_sel_hi:[1,0]
	v_pk_mul_f32 v[94:95], v[94:95], v[136:137] op_sel_hi:[1,0]
	v_pk_mul_f32 v[88:89], v[88:89], v[136:137] op_sel_hi:[1,0]
	v_pk_mul_f32 v[90:91], v[90:91], v[136:137] op_sel_hi:[1,0]
	v_pk_mul_f32 v[84:85], v[84:85], v[136:137] op_sel_hi:[1,0]
	v_pk_mul_f32 v[86:87], v[86:87], v[136:137] op_sel_hi:[1,0]
	v_pk_mul_f32 v[80:81], v[80:81], v[136:137] op_sel_hi:[1,0]
	v_pk_mul_f32 v[82:83], v[82:83], v[136:137] op_sel_hi:[1,0]
	v_cvt_pk_bf16_f32 v146, v92, v93
	v_cvt_pk_bf16_f32 v147, v94, v95
	v_cvt_pk_bf16_f32 v148, v88, v89
	v_cvt_pk_bf16_f32 v149, v90, v91
	global_store_dwordx4 v130, v[146:149], s[6:7] sc1
	v_cvt_pk_bf16_f32 v150, v84, v85
	v_cvt_pk_bf16_f32 v151, v86, v87
	v_cvt_pk_bf16_f32 v152, v80, v81
	v_cvt_pk_bf16_f32 v153, v82, v83
	global_store_dwordx4 v130, v[150:153], s[6:7] offset:256 sc1
	s_add_u32 s6, s6, s33
	s_addc_u32 s7, s7, 0
	v_pk_mul_f32 v[76:77], v[76:77], v[136:137] op_sel:[0,1] op_sel_hi:[1,1]
	v_pk_mul_f32 v[78:79], v[78:79], v[136:137] op_sel:[0,1] op_sel_hi:[1,1]
	v_pk_mul_f32 v[72:73], v[72:73], v[136:137] op_sel:[0,1] op_sel_hi:[1,1]
	v_pk_mul_f32 v[74:75], v[74:75], v[136:137] op_sel:[0,1] op_sel_hi:[1,1]
	v_pk_mul_f32 v[68:69], v[68:69], v[136:137] op_sel:[0,1] op_sel_hi:[1,1]
	v_pk_mul_f32 v[70:71], v[70:71], v[136:137] op_sel:[0,1] op_sel_hi:[1,1]
	v_pk_mul_f32 v[64:65], v[64:65], v[136:137] op_sel:[0,1] op_sel_hi:[1,1]
	v_pk_mul_f32 v[66:67], v[66:67], v[136:137] op_sel:[0,1] op_sel_hi:[1,1]
	v_cvt_pk_bf16_f32 v146, v76, v77
	v_cvt_pk_bf16_f32 v147, v78, v79
	v_cvt_pk_bf16_f32 v148, v72, v73
	v_cvt_pk_bf16_f32 v149, v74, v75
	global_store_dwordx4 v130, v[146:149], s[6:7] sc1
	v_cvt_pk_bf16_f32 v150, v68, v69
	v_cvt_pk_bf16_f32 v151, v70, v71
	v_cvt_pk_bf16_f32 v152, v64, v65
	v_cvt_pk_bf16_f32 v153, v66, v67
	global_store_dwordx4 v130, v[150:153], s[6:7] offset:256 sc1
	s_add_u32 s6, s6, s34
	s_addc_u32 s7, s7, 0
	v_pk_mul_f32 v[60:61], v[60:61], v[138:139] op_sel_hi:[1,0]
	v_pk_mul_f32 v[62:63], v[62:63], v[138:139] op_sel_hi:[1,0]
	v_pk_mul_f32 v[56:57], v[56:57], v[138:139] op_sel_hi:[1,0]
	v_pk_mul_f32 v[58:59], v[58:59], v[138:139] op_sel_hi:[1,0]
	v_pk_mul_f32 v[52:53], v[52:53], v[138:139] op_sel_hi:[1,0]
	v_pk_mul_f32 v[54:55], v[54:55], v[138:139] op_sel_hi:[1,0]
	v_pk_mul_f32 v[48:49], v[48:49], v[138:139] op_sel_hi:[1,0]
	v_pk_mul_f32 v[50:51], v[50:51], v[138:139] op_sel_hi:[1,0]
	v_cvt_pk_bf16_f32 v146, v60, v61
	v_cvt_pk_bf16_f32 v147, v62, v63
	v_cvt_pk_bf16_f32 v148, v56, v57
	v_cvt_pk_bf16_f32 v149, v58, v59
	global_store_dwordx4 v130, v[146:149], s[6:7] sc1
	v_cvt_pk_bf16_f32 v150, v52, v53
	v_cvt_pk_bf16_f32 v151, v54, v55
	v_cvt_pk_bf16_f32 v152, v48, v49
	v_cvt_pk_bf16_f32 v153, v50, v51
	global_store_dwordx4 v130, v[150:153], s[6:7] offset:256 sc1
	s_add_u32 s6, s6, s33
	s_addc_u32 s7, s7, 0
	v_pk_mul_f32 v[44:45], v[44:45], v[138:139] op_sel:[0,1] op_sel_hi:[1,1]
	v_pk_mul_f32 v[46:47], v[46:47], v[138:139] op_sel:[0,1] op_sel_hi:[1,1]
	v_pk_mul_f32 v[40:41], v[40:41], v[138:139] op_sel:[0,1] op_sel_hi:[1,1]
	v_pk_mul_f32 v[42:43], v[42:43], v[138:139] op_sel:[0,1] op_sel_hi:[1,1]
	v_pk_mul_f32 v[36:37], v[36:37], v[138:139] op_sel:[0,1] op_sel_hi:[1,1]
	v_pk_mul_f32 v[38:39], v[38:39], v[138:139] op_sel:[0,1] op_sel_hi:[1,1]
	v_pk_mul_f32 v[32:33], v[32:33], v[138:139] op_sel:[0,1] op_sel_hi:[1,1]
	v_pk_mul_f32 v[34:35], v[34:35], v[138:139] op_sel:[0,1] op_sel_hi:[1,1]
	v_cvt_pk_bf16_f32 v146, v44, v45
	v_cvt_pk_bf16_f32 v147, v46, v47
	v_cvt_pk_bf16_f32 v148, v40, v41
	v_cvt_pk_bf16_f32 v149, v42, v43
	global_store_dwordx4 v130, v[146:149], s[6:7] sc1
	v_cvt_pk_bf16_f32 v150, v36, v37
	v_cvt_pk_bf16_f32 v151, v38, v39
	v_cvt_pk_bf16_f32 v152, v32, v33
	v_cvt_pk_bf16_f32 v153, v34, v35
	global_store_dwordx4 v130, v[150:153], s[6:7] offset:256 sc1
	s_add_u32 s6, s6, s33
	s_addc_u32 s7, s7, 0
	v_pk_mul_f32 v[28:29], v[28:29], v[140:141] op_sel_hi:[1,0]
	v_pk_mul_f32 v[30:31], v[30:31], v[140:141] op_sel_hi:[1,0]
	v_pk_mul_f32 v[24:25], v[24:25], v[140:141] op_sel_hi:[1,0]
	v_pk_mul_f32 v[26:27], v[26:27], v[140:141] op_sel_hi:[1,0]
	v_pk_mul_f32 v[20:21], v[20:21], v[140:141] op_sel_hi:[1,0]
	v_pk_mul_f32 v[22:23], v[22:23], v[140:141] op_sel_hi:[1,0]
	v_pk_mul_f32 v[16:17], v[16:17], v[140:141] op_sel_hi:[1,0]
	v_pk_mul_f32 v[18:19], v[18:19], v[140:141] op_sel_hi:[1,0]
	v_cvt_pk_bf16_f32 v146, v28, v29
	v_cvt_pk_bf16_f32 v147, v30, v31
	v_cvt_pk_bf16_f32 v148, v24, v25
	v_cvt_pk_bf16_f32 v149, v26, v27
	global_store_dwordx4 v130, v[146:149], s[6:7] sc1
	v_cvt_pk_bf16_f32 v150, v20, v21
	v_cvt_pk_bf16_f32 v151, v22, v23
	v_cvt_pk_bf16_f32 v152, v16, v17
	v_cvt_pk_bf16_f32 v153, v18, v19
	global_store_dwordx4 v130, v[150:153], s[6:7] offset:256 sc1
	s_add_u32 s6, s6, s33
	s_addc_u32 s7, s7, 0
	v_pk_mul_f32 v[12:13], v[12:13], v[140:141] op_sel:[0,1] op_sel_hi:[1,1]
	v_pk_mul_f32 v[14:15], v[14:15], v[140:141] op_sel:[0,1] op_sel_hi:[1,1]
	v_pk_mul_f32 v[4:5], v[4:5], v[140:141] op_sel:[0,1] op_sel_hi:[1,1]
	v_pk_mul_f32 v[6:7], v[6:7], v[140:141] op_sel:[0,1] op_sel_hi:[1,1]
	v_pk_mul_f32 v[8:9], v[8:9], v[140:141] op_sel:[0,1] op_sel_hi:[1,1]
	v_pk_mul_f32 v[10:11], v[10:11], v[140:141] op_sel:[0,1] op_sel_hi:[1,1]
	v_pk_mul_f32 v[0:1], v[0:1], v[140:141] op_sel:[0,1] op_sel_hi:[1,1]
	v_pk_mul_f32 v[2:3], v[2:3], v[140:141] op_sel:[0,1] op_sel_hi:[1,1]
	v_cvt_pk_bf16_f32 v146, v12, v13
	v_cvt_pk_bf16_f32 v147, v14, v15
	v_cvt_pk_bf16_f32 v148, v4, v5
	v_cvt_pk_bf16_f32 v149, v6, v7
	global_store_dwordx4 v130, v[146:149], s[6:7] sc1
	v_cvt_pk_bf16_f32 v150, v8, v9
	v_cvt_pk_bf16_f32 v151, v10, v11
	v_cvt_pk_bf16_f32 v152, v0, v1
	v_cvt_pk_bf16_f32 v153, v2, v3
	global_store_dwordx4 v130, v[150:153], s[6:7] offset:256 sc1
	s_branch .LBB0_686

.Lq1_common:
	v_lshl_add_u32 v130, v191, 4, v130
	s_add_u32 s6, s4, s35
	s_addc_u32 s7, s5, 0
	s_waitcnt vmcnt(0)
	v_add_f32_e32 v142, v154, v155
	v_add_f32_e32 v143, v156, v157
	v_add_f32_e32 v144, v158, v159
	v_add_f32_e32 v145, v160, v161
	v_add_f32_e32 v142, v142, v143
	v_add_f32_e32 v144, v144, v145
	v_add_f32_e32 v142, v142, v144
	v_fmamk_f32 v134, v142, 0x3b2aaaab, v242
	v_add_f32_e32 v142, v162, v163
	v_add_f32_e32 v143, v164, v165
	v_add_f32_e32 v144, v166, v167
	v_add_f32_e32 v145, v168, v169
	v_add_f32_e32 v142, v142, v143
	v_add_f32_e32 v144, v144, v145
	v_add_f32_e32 v142, v142, v144
	v_fmamk_f32 v135, v142, 0x3b2aaaab, v242
	v_add_f32_e32 v142, v170, v171
	v_add_f32_e32 v143, v172, v173
	v_add_f32_e32 v144, v174, v175
	v_add_f32_e32 v145, v176, v177
	v_add_f32_e32 v142, v142, v143
	v_add_f32_e32 v144, v144, v145
	v_add_f32_e32 v142, v142, v144
	v_fmamk_f32 v136, v142, 0x3b2aaaab, v242
	v_add_f32_e32 v142, v178, v179
	v_add_f32_e32 v143, v180, v181
	v_add_f32_e32 v144, v202, v203
	v_add_f32_e32 v145, v204, v205
	v_add_f32_e32 v142, v142, v143
	v_add_f32_e32 v144, v144, v145
	v_add_f32_e32 v142, v142, v144
	v_fmamk_f32 v137, v142, 0x3b2aaaab, v242
	v_add_f32_e32 v142, v206, v207
	v_add_f32_e32 v143, v208, v209
	v_add_f32_e32 v144, v210, v211
	v_add_f32_e32 v145, v212, v213
	v_add_f32_e32 v142, v142, v143
	v_add_f32_e32 v144, v144, v145
	v_add_f32_e32 v142, v142, v144
	v_fmamk_f32 v138, v142, 0x3b2aaaab, v242
	v_add_f32_e32 v142, v214, v215
	v_add_f32_e32 v143, v216, v217
	v_add_f32_e32 v144, v218, v219
	v_add_f32_e32 v145, v220, v221
	v_add_f32_e32 v142, v142, v143
	v_add_f32_e32 v144, v144, v145
	v_add_f32_e32 v142, v142, v144
	v_fmamk_f32 v139, v142, 0x3b2aaaab, v242
	v_add_f32_e32 v142, v222, v223
	v_add_f32_e32 v143, v224, v225
	v_add_f32_e32 v144, v226, v227
	v_add_f32_e32 v145, v228, v229
	v_add_f32_e32 v142, v142, v143
	v_add_f32_e32 v144, v144, v145
	v_add_f32_e32 v142, v142, v144
	v_fmamk_f32 v140, v142, 0x3b2aaaab, v242
	v_add_f32_e32 v142, v230, v231
	v_add_f32_e32 v143, v232, v233
	v_add_f32_e32 v144, v234, v235
	v_add_f32_e32 v145, v236, v237
	v_add_f32_e32 v142, v142, v143
	v_add_f32_e32 v144, v144, v145
	v_add_f32_e32 v142, v142, v144
	v_fmamk_f32 v141, v142, 0x3b2aaaab, v242
	v_rsq_f32_e32 v134, v134
	v_rsq_f32_e32 v135, v135
	v_rsq_f32_e32 v136, v136
	v_rsq_f32_e32 v137, v137
	v_rsq_f32_e32 v138, v138
	v_rsq_f32_e32 v139, v139
	v_rsq_f32_e32 v140, v140
	v_rsq_f32_e32 v141, v141
	s_nop 0
	v_mul_f32_e32 v134, 0x3e16c740, v134
	v_mul_f32_e32 v135, 0x3e16c740, v135
	v_mul_f32_e32 v136, 0x3e16c740, v136
	v_mul_f32_e32 v137, 0x3e16c740, v137
	v_mul_f32_e32 v138, 0x3e16c740, v138
	v_mul_f32_e32 v139, 0x3e16c740, v139
	v_mul_f32_e32 v140, 0x3e16c740, v140
	v_mul_f32_e32 v141, 0x3e16c740, v141
	s_cmp_lt_u32 s74, 4
	s_cbranch_scc1 .Lq1_plain
	s_cmp_lt_u32 s48, 32
	s_cbranch_scc1 .Lq1_plain
	s_sub_u32 s36, s48, 32
	s_and_b32 s36, s36, 3
	s_lshl_b32 s36, s36, 8
	s_add_u32 s36, s36, s49
	s_lshl_b32 s36, s36, 6
	s_add_u32 s36, s36, 0x1c0000
	s_add_u32 s8, s4, s36
	s_addc_u32 s9, s5, 0
	v_lshlrev_b32_e32 v132, 6, v189
	v_lshl_add_u32 v132, v191, 4, v132
	v_add_u32_e32 v133, 0x10000, v132
	global_load_dwordx4 v[218:221], v132, s[8:9]
	global_load_dwordx4 v[222:225], v133, s[8:9]
	s_add_u32 s8, s8, 0x400
	s_addc_u32 s9, s9, 0
	global_load_dwordx4 v[226:229], v132, s[8:9]
	global_load_dwordx4 v[230:233], v133, s[8:9]
	v_pk_mul_f32 v[126:127], v[126:127], v[134:135] op_sel_hi:[1,0]
	v_pk_mul_f32 v[128:129], v[128:129], v[134:135] op_sel_hi:[1,0]
	v_pk_mul_f32 v[122:123], v[122:123], v[134:135] op_sel_hi:[1,0]
	v_pk_mul_f32 v[124:125], v[124:125], v[134:135] op_sel_hi:[1,0]
	v_pk_mul_f32 v[118:119], v[118:119], v[134:135] op_sel_hi:[1,0]
	v_pk_mul_f32 v[120:121], v[120:121], v[134:135] op_sel_hi:[1,0]
	v_pk_mul_f32 v[114:115], v[114:115], v[134:135] op_sel_hi:[1,0]
	v_pk_mul_f32 v[116:117], v[116:117], v[134:135] op_sel_hi:[1,0]
	s_waitcnt vmcnt(2)
	v_pk_mul_f32 v[142:143], v[126:127], v[222:223] op_sel:[1,0] op_sel_hi:[0,0]
	v_pk_fma_f32 v[126:127], v[126:127], v[218:219], v[142:143] op_sel:[0,0,0] op_sel_hi:[1,0,1] neg_lo:[0,0,1]
	v_pk_mul_f32 v[142:143], v[128:129], v[222:223] op_sel:[1,1] op_sel_hi:[0,1]
	v_pk_fma_f32 v[128:129], v[128:129], v[218:219], v[142:143] op_sel:[0,1,0] op_sel_hi:[1,1,1] neg_lo:[0,0,1]
	v_pk_mul_f32 v[142:143], v[122:123], v[224:225] op_sel:[1,0] op_sel_hi:[0,0]
	v_pk_fma_f32 v[122:123], v[122:123], v[220:221], v[142:143] op_sel:[0,0,0] op_sel_hi:[1,0,1] neg_lo:[0,0,1]
	v_pk_mul_f32 v[142:143], v[124:125], v[224:225] op_sel:[1,1] op_sel_hi:[0,1]
	v_pk_fma_f32 v[124:125], v[124:125], v[220:221], v[142:143] op_sel:[0,1,0] op_sel_hi:[1,1,1] neg_lo:[0,0,1]
	v_cvt_pk_bf16_f32 v146, v126, v127
	v_cvt_pk_bf16_f32 v147, v128, v129
	v_cvt_pk_bf16_f32 v148, v122, v123
	v_cvt_pk_bf16_f32 v149, v124, v125
	global_store_dwordx4 v130, v[146:149], s[6:7] sc1
	v_pk_mul_f32 v[142:143], v[118:119], v[222:223] op_sel:[1,0] op_sel_hi:[0,0]
	v_pk_fma_f32 v[118:119], v[118:119], v[218:219], v[142:143] op_sel:[0,0,0] op_sel_hi:[1,0,1] neg_lo:[0,0,1]
	v_pk_mul_f32 v[142:143], v[120:121], v[222:223] op_sel:[1,1] op_sel_hi:[0,1]
	v_pk_fma_f32 v[120:121], v[120:121], v[218:219], v[142:143] op_sel:[0,1,0] op_sel_hi:[1,1,1] neg_lo:[0,0,1]
	v_pk_mul_f32 v[142:143], v[114:115], v[224:225] op_sel:[1,0] op_sel_hi:[0,0]
	v_pk_fma_f32 v[114:115], v[114:115], v[220:221], v[142:143] op_sel:[0,0,0] op_sel_hi:[1,0,1] neg_lo:[0,0,1]
	v_pk_mul_f32 v[142:143], v[116:117], v[224:225] op_sel:[1,1] op_sel_hi:[0,1]
	v_pk_fma_f32 v[116:117], v[116:117], v[220:221], v[142:143] op_sel:[0,1,0] op_sel_hi:[1,1,1] neg_lo:[0,0,1]
	v_cvt_pk_bf16_f32 v150, v118, v119
	v_cvt_pk_bf16_f32 v151, v120, v121
	v_cvt_pk_bf16_f32 v152, v114, v115
	v_cvt_pk_bf16_f32 v153, v116, v117
	global_store_dwordx4 v130, v[150:153], s[6:7] offset:256 sc1
	s_add_u32 s6, s6, s33
	s_addc_u32 s7, s7, 0
	s_add_u32 s8, s8, 0x400
	s_addc_u32 s9, s9, 0
	global_load_dwordx4 v[218:221], v132, s[8:9]
	global_load_dwordx4 v[222:225], v133, s[8:9]
	v_pk_mul_f32 v[108:109], v[108:109], v[134:135] op_sel:[0,1] op_sel_hi:[1,1]
	v_pk_mul_f32 v[110:111], v[110:111], v[134:135] op_sel:[0,1] op_sel_hi:[1,1]
	v_pk_mul_f32 v[104:105], v[104:105], v[134:135] op_sel:[0,1] op_sel_hi:[1,1]
	v_pk_mul_f32 v[106:107], v[106:107], v[134:135] op_sel:[0,1] op_sel_hi:[1,1]
	v_pk_mul_f32 v[100:101], v[100:101], v[134:135] op_sel:[0,1] op_sel_hi:[1,1]
	v_pk_mul_f32 v[102:103], v[102:103], v[134:135] op_sel:[0,1] op_sel_hi:[1,1]
	v_pk_mul_f32 v[96:97], v[96:97], v[134:135] op_sel:[0,1] op_sel_hi:[1,1]
	v_pk_mul_f32 v[98:99], v[98:99], v[134:135] op_sel:[0,1] op_sel_hi:[1,1]
	s_waitcnt vmcnt(4)
	v_pk_mul_f32 v[142:143], v[108:109], v[230:231] op_sel:[1,0] op_sel_hi:[0,0]
	v_pk_fma_f32 v[108:109], v[108:109], v[226:227], v[142:143] op_sel:[0,0,0] op_sel_hi:[1,0,1] neg_lo:[0,0,1]
	v_pk_mul_f32 v[142:143], v[110:111], v[230:231] op_sel:[1,1] op_sel_hi:[0,1]
	v_pk_fma_f32 v[110:111], v[110:111], v[226:227], v[142:143] op_sel:[0,1,0] op_sel_hi:[1,1,1] neg_lo:[0,0,1]
	v_pk_mul_f32 v[142:143], v[104:105], v[232:233] op_sel:[1,0] op_sel_hi:[0,0]
	v_pk_fma_f32 v[104:105], v[104:105], v[228:229], v[142:143] op_sel:[0,0,0] op_sel_hi:[1,0,1] neg_lo:[0,0,1]
	v_pk_mul_f32 v[142:143], v[106:107], v[232:233] op_sel:[1,1] op_sel_hi:[0,1]
	v_pk_fma_f32 v[106:107], v[106:107], v[228:229], v[142:143] op_sel:[0,1,0] op_sel_hi:[1,1,1] neg_lo:[0,0,1]
	v_cvt_pk_bf16_f32 v146, v108, v109
	v_cvt_pk_bf16_f32 v147, v110, v111
	v_cvt_pk_bf16_f32 v148, v104, v105
	v_cvt_pk_bf16_f32 v149, v106, v107
	global_store_dwordx4 v130, v[146:149], s[6:7] sc1
	v_pk_mul_f32 v[142:143], v[100:101], v[230:231] op_sel:[1,0] op_sel_hi:[0,0]
	v_pk_fma_f32 v[100:101], v[100:101], v[226:227], v[142:143] op_sel:[0,0,0] op_sel_hi:[1,0,1] neg_lo:[0,0,1]
	v_pk_mul_f32 v[142:143], v[102:103], v[230:231] op_sel:[1,1] op_sel_hi:[0,1]
	v_pk_fma_f32 v[102:103], v[102:103], v[226:227], v[142:143] op_sel:[0,1,0] op_sel_hi:[1,1,1] neg_lo:[0,0,1]
	v_pk_mul_f32 v[142:143], v[96:97], v[232:233] op_sel:[1,0] op_sel_hi:[0,0]
	v_pk_fma_f32 v[96:97], v[96:97], v[228:229], v[142:143] op_sel:[0,0,0] op_sel_hi:[1,0,1] neg_lo:[0,0,1]
	v_pk_mul_f32 v[142:143], v[98:99], v[232:233] op_sel:[1,1] op_sel_hi:[0,1]
	v_pk_fma_f32 v[98:99], v[98:99], v[228:229], v[142:143] op_sel:[0,1,0] op_sel_hi:[1,1,1] neg_lo:[0,0,1]
	v_cvt_pk_bf16_f32 v150, v100, v101
	v_cvt_pk_bf16_f32 v151, v102, v103
	v_cvt_pk_bf16_f32 v152, v96, v97
	v_cvt_pk_bf16_f32 v153, v98, v99
	global_store_dwordx4 v130, v[150:153], s[6:7] offset:256 sc1
	s_add_u32 s6, s6, s33
	s_addc_u32 s7, s7, 0
	s_add_u32 s8, s8, 0x400
	s_addc_u32 s9, s9, 0
	global_load_dwordx4 v[226:229], v132, s[8:9]
	global_load_dwordx4 v[230:233], v133, s[8:9]
	v_pk_mul_f32 v[92:93], v[92:93], v[136:137] op_sel_hi:[1,0]
	v_pk_mul_f32 v[94:95], v[94:95], v[136:137] op_sel_hi:[1,0]
	v_pk_mul_f32 v[88:89], v[88:89], v[136:137] op_sel_hi:[1,0]
	v_pk_mul_f32 v[90:91], v[90:91], v[136:137] op_sel_hi:[1,0]
	v_pk_mul_f32 v[84:85], v[84:85], v[136:137] op_sel_hi:[1,0]
	v_pk_mul_f32 v[86:87], v[86:87], v[136:137] op_sel_hi:[1,0]
	v_pk_mul_f32 v[80:81], v[80:81], v[136:137] op_sel_hi:[1,0]
	v_pk_mul_f32 v[82:83], v[82:83], v[136:137] op_sel_hi:[1,0]
	s_waitcnt vmcnt(4)
	v_pk_mul_f32 v[142:143], v[92:93], v[222:223] op_sel:[1,0] op_sel_hi:[0,0]
	v_pk_fma_f32 v[92:93], v[92:93], v[218:219], v[142:143] op_sel:[0,0,0] op_sel_hi:[1,0,1] neg_lo:[0,0,1]
	v_pk_mul_f32 v[142:143], v[94:95], v[222:223] op_sel:[1,1] op_sel_hi:[0,1]
	v_pk_fma_f32 v[94:95], v[94:95], v[218:219], v[142:143] op_sel:[0,1,0] op_sel_hi:[1,1,1] neg_lo:[0,0,1]
	v_pk_mul_f32 v[142:143], v[88:89], v[224:225] op_sel:[1,0] op_sel_hi:[0,0]
	v_pk_fma_f32 v[88:89], v[88:89], v[220:221], v[142:143] op_sel:[0,0,0] op_sel_hi:[1,0,1] neg_lo:[0,0,1]
	v_pk_mul_f32 v[142:143], v[90:91], v[224:225] op_sel:[1,1] op_sel_hi:[0,1]
	v_pk_fma_f32 v[90:91], v[90:91], v[220:221], v[142:143] op_sel:[0,1,0] op_sel_hi:[1,1,1] neg_lo:[0,0,1]
	v_cvt_pk_bf16_f32 v146, v92, v93
	v_cvt_pk_bf16_f32 v147, v94, v95
	v_cvt_pk_bf16_f32 v148, v88, v89
	v_cvt_pk_bf16_f32 v149, v90, v91
	global_store_dwordx4 v130, v[146:149], s[6:7] sc1
	v_pk_mul_f32 v[142:143], v[84:85], v[222:223] op_sel:[1,0] op_sel_hi:[0,0]
	v_pk_fma_f32 v[84:85], v[84:85], v[218:219], v[142:143] op_sel:[0,0,0] op_sel_hi:[1,0,1] neg_lo:[0,0,1]
	v_pk_mul_f32 v[142:143], v[86:87], v[222:223] op_sel:[1,1] op_sel_hi:[0,1]
	v_pk_fma_f32 v[86:87], v[86:87], v[218:219], v[142:143] op_sel:[0,1,0] op_sel_hi:[1,1,1] neg_lo:[0,0,1]
	v_pk_mul_f32 v[142:143], v[80:81], v[224:225] op_sel:[1,0] op_sel_hi:[0,0]
	v_pk_fma_f32 v[80:81], v[80:81], v[220:221], v[142:143] op_sel:[0,0,0] op_sel_hi:[1,0,1] neg_lo:[0,0,1]
	v_pk_mul_f32 v[142:143], v[82:83], v[224:225] op_sel:[1,1] op_sel_hi:[0,1]
	v_pk_fma_f32 v[82:83], v[82:83], v[220:221], v[142:143] op_sel:[0,1,0] op_sel_hi:[1,1,1] neg_lo:[0,0,1]
	v_cvt_pk_bf16_f32 v150, v84, v85
	v_cvt_pk_bf16_f32 v151, v86, v87
	v_cvt_pk_bf16_f32 v152, v80, v81
	v_cvt_pk_bf16_f32 v153, v82, v83
	global_store_dwordx4 v130, v[150:153], s[6:7] offset:256 sc1
	s_add_u32 s6, s6, s33
	s_addc_u32 s7, s7, 0
	s_add_u32 s8, s8, 0x1400
	s_addc_u32 s9, s9, 0
	global_load_dwordx4 v[218:221], v132, s[8:9]
	global_load_dwordx4 v[222:225], v133, s[8:9]
	v_pk_mul_f32 v[76:77], v[76:77], v[136:137] op_sel:[0,1] op_sel_hi:[1,1]
	v_pk_mul_f32 v[78:79], v[78:79], v[136:137] op_sel:[0,1] op_sel_hi:[1,1]
	v_pk_mul_f32 v[72:73], v[72:73], v[136:137] op_sel:[0,1] op_sel_hi:[1,1]
	v_pk_mul_f32 v[74:75], v[74:75], v[136:137] op_sel:[0,1] op_sel_hi:[1,1]
	v_pk_mul_f32 v[68:69], v[68:69], v[136:137] op_sel:[0,1] op_sel_hi:[1,1]
	v_pk_mul_f32 v[70:71], v[70:71], v[136:137] op_sel:[0,1] op_sel_hi:[1,1]
	v_pk_mul_f32 v[64:65], v[64:65], v[136:137] op_sel:[0,1] op_sel_hi:[1,1]
	v_pk_mul_f32 v[66:67], v[66:67], v[136:137] op_sel:[0,1] op_sel_hi:[1,1]
	s_waitcnt vmcnt(4)
	v_pk_mul_f32 v[142:143], v[76:77], v[230:231] op_sel:[1,0] op_sel_hi:[0,0]
	v_pk_fma_f32 v[76:77], v[76:77], v[226:227], v[142:143] op_sel:[0,0,0] op_sel_hi:[1,0,1] neg_lo:[0,0,1]
	v_pk_mul_f32 v[142:143], v[78:79], v[230:231] op_sel:[1,1] op_sel_hi:[0,1]
	v_pk_fma_f32 v[78:79], v[78:79], v[226:227], v[142:143] op_sel:[0,1,0] op_sel_hi:[1,1,1] neg_lo:[0,0,1]
	v_pk_mul_f32 v[142:143], v[72:73], v[232:233] op_sel:[1,0] op_sel_hi:[0,0]
	v_pk_fma_f32 v[72:73], v[72:73], v[228:229], v[142:143] op_sel:[0,0,0] op_sel_hi:[1,0,1] neg_lo:[0,0,1]
	v_pk_mul_f32 v[142:143], v[74:75], v[232:233] op_sel:[1,1] op_sel_hi:[0,1]
	v_pk_fma_f32 v[74:75], v[74:75], v[228:229], v[142:143] op_sel:[0,1,0] op_sel_hi:[1,1,1] neg_lo:[0,0,1]
	v_cvt_pk_bf16_f32 v146, v76, v77
	v_cvt_pk_bf16_f32 v147, v78, v79
	v_cvt_pk_bf16_f32 v148, v72, v73
	v_cvt_pk_bf16_f32 v149, v74, v75
	global_store_dwordx4 v130, v[146:149], s[6:7] sc1
	v_pk_mul_f32 v[142:143], v[68:69], v[230:231] op_sel:[1,0] op_sel_hi:[0,0]
	v_pk_fma_f32 v[68:69], v[68:69], v[226:227], v[142:143] op_sel:[0,0,0] op_sel_hi:[1,0,1] neg_lo:[0,0,1]
	v_pk_mul_f32 v[142:143], v[70:71], v[230:231] op_sel:[1,1] op_sel_hi:[0,1]
	v_pk_fma_f32 v[70:71], v[70:71], v[226:227], v[142:143] op_sel:[0,1,0] op_sel_hi:[1,1,1] neg_lo:[0,0,1]
	v_pk_mul_f32 v[142:143], v[64:65], v[232:233] op_sel:[1,0] op_sel_hi:[0,0]
	v_pk_fma_f32 v[64:65], v[64:65], v[228:229], v[142:143] op_sel:[0,0,0] op_sel_hi:[1,0,1] neg_lo:[0,0,1]
	v_pk_mul_f32 v[142:143], v[66:67], v[232:233] op_sel:[1,1] op_sel_hi:[0,1]
	v_pk_fma_f32 v[66:67], v[66:67], v[228:229], v[142:143] op_sel:[0,1,0] op_sel_hi:[1,1,1] neg_lo:[0,0,1]
	v_cvt_pk_bf16_f32 v150, v68, v69
	v_cvt_pk_bf16_f32 v151, v70, v71
	v_cvt_pk_bf16_f32 v152, v64, v65
	v_cvt_pk_bf16_f32 v153, v66, v67
	global_store_dwordx4 v130, v[150:153], s[6:7] offset:256 sc1
	s_add_u32 s6, s6, s34
	s_addc_u32 s7, s7, 0
	s_add_u32 s8, s8, 0x400
	s_addc_u32 s9, s9, 0
	global_load_dwordx4 v[226:229], v132, s[8:9]
	global_load_dwordx4 v[230:233], v133, s[8:9]
	v_pk_mul_f32 v[60:61], v[60:61], v[138:139] op_sel_hi:[1,0]
	v_pk_mul_f32 v[62:63], v[62:63], v[138:139] op_sel_hi:[1,0]
	v_pk_mul_f32 v[56:57], v[56:57], v[138:139] op_sel_hi:[1,0]
	v_pk_mul_f32 v[58:59], v[58:59], v[138:139] op_sel_hi:[1,0]
	v_pk_mul_f32 v[52:53], v[52:53], v[138:139] op_sel_hi:[1,0]
	v_pk_mul_f32 v[54:55], v[54:55], v[138:139] op_sel_hi:[1,0]
	v_pk_mul_f32 v[48:49], v[48:49], v[138:139] op_sel_hi:[1,0]
	v_pk_mul_f32 v[50:51], v[50:51], v[138:139] op_sel_hi:[1,0]
	s_waitcnt vmcnt(4)
	v_pk_mul_f32 v[142:143], v[60:61], v[222:223] op_sel:[1,0] op_sel_hi:[0,0]
	v_pk_fma_f32 v[60:61], v[60:61], v[218:219], v[142:143] op_sel:[0,0,0] op_sel_hi:[1,0,1] neg_lo:[0,0,1]
	v_pk_mul_f32 v[142:143], v[62:63], v[222:223] op_sel:[1,1] op_sel_hi:[0,1]
	v_pk_fma_f32 v[62:63], v[62:63], v[218:219], v[142:143] op_sel:[0,1,0] op_sel_hi:[1,1,1] neg_lo:[0,0,1]
	v_pk_mul_f32 v[142:143], v[56:57], v[224:225] op_sel:[1,0] op_sel_hi:[0,0]
	v_pk_fma_f32 v[56:57], v[56:57], v[220:221], v[142:143] op_sel:[0,0,0] op_sel_hi:[1,0,1] neg_lo:[0,0,1]
	v_pk_mul_f32 v[142:143], v[58:59], v[224:225] op_sel:[1,1] op_sel_hi:[0,1]
	v_pk_fma_f32 v[58:59], v[58:59], v[220:221], v[142:143] op_sel:[0,1,0] op_sel_hi:[1,1,1] neg_lo:[0,0,1]
	v_cvt_pk_bf16_f32 v146, v60, v61
	v_cvt_pk_bf16_f32 v147, v62, v63
	v_cvt_pk_bf16_f32 v148, v56, v57
	v_cvt_pk_bf16_f32 v149, v58, v59
	global_store_dwordx4 v130, v[146:149], s[6:7] sc1
	v_pk_mul_f32 v[142:143], v[52:53], v[222:223] op_sel:[1,0] op_sel_hi:[0,0]
	v_pk_fma_f32 v[52:53], v[52:53], v[218:219], v[142:143] op_sel:[0,0,0] op_sel_hi:[1,0,1] neg_lo:[0,0,1]
	v_pk_mul_f32 v[142:143], v[54:55], v[222:223] op_sel:[1,1] op_sel_hi:[0,1]
	v_pk_fma_f32 v[54:55], v[54:55], v[218:219], v[142:143] op_sel:[0,1,0] op_sel_hi:[1,1,1] neg_lo:[0,0,1]
	v_pk_mul_f32 v[142:143], v[48:49], v[224:225] op_sel:[1,0] op_sel_hi:[0,0]
	v_pk_fma_f32 v[48:49], v[48:49], v[220:221], v[142:143] op_sel:[0,0,0] op_sel_hi:[1,0,1] neg_lo:[0,0,1]
	v_pk_mul_f32 v[142:143], v[50:51], v[224:225] op_sel:[1,1] op_sel_hi:[0,1]
	v_pk_fma_f32 v[50:51], v[50:51], v[220:221], v[142:143] op_sel:[0,1,0] op_sel_hi:[1,1,1] neg_lo:[0,0,1]
	v_cvt_pk_bf16_f32 v150, v52, v53
	v_cvt_pk_bf16_f32 v151, v54, v55
	v_cvt_pk_bf16_f32 v152, v48, v49
	v_cvt_pk_bf16_f32 v153, v50, v51
	global_store_dwordx4 v130, v[150:153], s[6:7] offset:256 sc1
	s_add_u32 s6, s6, s33
	s_addc_u32 s7, s7, 0
	s_add_u32 s8, s8, 0x400
	s_addc_u32 s9, s9, 0
	global_load_dwordx4 v[218:221], v132, s[8:9]
	global_load_dwordx4 v[222:225], v133, s[8:9]
	v_pk_mul_f32 v[44:45], v[44:45], v[138:139] op_sel:[0,1] op_sel_hi:[1,1]
	v_pk_mul_f32 v[46:47], v[46:47], v[138:139] op_sel:[0,1] op_sel_hi:[1,1]
	v_pk_mul_f32 v[40:41], v[40:41], v[138:139] op_sel:[0,1] op_sel_hi:[1,1]
	v_pk_mul_f32 v[42:43], v[42:43], v[138:139] op_sel:[0,1] op_sel_hi:[1,1]
	v_pk_mul_f32 v[36:37], v[36:37], v[138:139] op_sel:[0,1] op_sel_hi:[1,1]
	v_pk_mul_f32 v[38:39], v[38:39], v[138:139] op_sel:[0,1] op_sel_hi:[1,1]
	v_pk_mul_f32 v[32:33], v[32:33], v[138:139] op_sel:[0,1] op_sel_hi:[1,1]
	v_pk_mul_f32 v[34:35], v[34:35], v[138:139] op_sel:[0,1] op_sel_hi:[1,1]
	s_waitcnt vmcnt(4)
	v_pk_mul_f32 v[142:143], v[44:45], v[230:231] op_sel:[1,0] op_sel_hi:[0,0]
	v_pk_fma_f32 v[44:45], v[44:45], v[226:227], v[142:143] op_sel:[0,0,0] op_sel_hi:[1,0,1] neg_lo:[0,0,1]
	v_pk_mul_f32 v[142:143], v[46:47], v[230:231] op_sel:[1,1] op_sel_hi:[0,1]
	v_pk_fma_f32 v[46:47], v[46:47], v[226:227], v[142:143] op_sel:[0,1,0] op_sel_hi:[1,1,1] neg_lo:[0,0,1]
	v_pk_mul_f32 v[142:143], v[40:41], v[232:233] op_sel:[1,0] op_sel_hi:[0,0]
	v_pk_fma_f32 v[40:41], v[40:41], v[228:229], v[142:143] op_sel:[0,0,0] op_sel_hi:[1,0,1] neg_lo:[0,0,1]
	v_pk_mul_f32 v[142:143], v[42:43], v[232:233] op_sel:[1,1] op_sel_hi:[0,1]
	v_pk_fma_f32 v[42:43], v[42:43], v[228:229], v[142:143] op_sel:[0,1,0] op_sel_hi:[1,1,1] neg_lo:[0,0,1]
	v_cvt_pk_bf16_f32 v146, v44, v45
	v_cvt_pk_bf16_f32 v147, v46, v47
	v_cvt_pk_bf16_f32 v148, v40, v41
	v_cvt_pk_bf16_f32 v149, v42, v43
	global_store_dwordx4 v130, v[146:149], s[6:7] sc1
	v_pk_mul_f32 v[142:143], v[36:37], v[230:231] op_sel:[1,0] op_sel_hi:[0,0]
	v_pk_fma_f32 v[36:37], v[36:37], v[226:227], v[142:143] op_sel:[0,0,0] op_sel_hi:[1,0,1] neg_lo:[0,0,1]
	v_pk_mul_f32 v[142:143], v[38:39], v[230:231] op_sel:[1,1] op_sel_hi:[0,1]
	v_pk_fma_f32 v[38:39], v[38:39], v[226:227], v[142:143] op_sel:[0,1,0] op_sel_hi:[1,1,1] neg_lo:[0,0,1]
	v_pk_mul_f32 v[142:143], v[32:33], v[232:233] op_sel:[1,0] op_sel_hi:[0,0]
	v_pk_fma_f32 v[32:33], v[32:33], v[228:229], v[142:143] op_sel:[0,0,0] op_sel_hi:[1,0,1] neg_lo:[0,0,1]
	v_pk_mul_f32 v[142:143], v[34:35], v[232:233] op_sel:[1,1] op_sel_hi:[0,1]
	v_pk_fma_f32 v[34:35], v[34:35], v[228:229], v[142:143] op_sel:[0,1,0] op_sel_hi:[1,1,1] neg_lo:[0,0,1]
	v_cvt_pk_bf16_f32 v150, v36, v37
	v_cvt_pk_bf16_f32 v151, v38, v39
	v_cvt_pk_bf16_f32 v152, v32, v33
	v_cvt_pk_bf16_f32 v153, v34, v35
	global_store_dwordx4 v130, v[150:153], s[6:7] offset:256 sc1
	s_add_u32 s6, s6, s33
	s_addc_u32 s7, s7, 0
	s_add_u32 s8, s8, 0x400
	s_addc_u32 s9, s9, 0
	global_load_dwordx4 v[226:229], v132, s[8:9]
	global_load_dwordx4 v[230:233], v133, s[8:9]
	v_pk_mul_f32 v[28:29], v[28:29], v[140:141] op_sel_hi:[1,0]
	v_pk_mul_f32 v[30:31], v[30:31], v[140:141] op_sel_hi:[1,0]
	v_pk_mul_f32 v[24:25], v[24:25], v[140:141] op_sel_hi:[1,0]
	v_pk_mul_f32 v[26:27], v[26:27], v[140:141] op_sel_hi:[1,0]
	v_pk_mul_f32 v[20:21], v[20:21], v[140:141] op_sel_hi:[1,0]
	v_pk_mul_f32 v[22:23], v[22:23], v[140:141] op_sel_hi:[1,0]
	v_pk_mul_f32 v[16:17], v[16:17], v[140:141] op_sel_hi:[1,0]
	v_pk_mul_f32 v[18:19], v[18:19], v[140:141] op_sel_hi:[1,0]
	s_waitcnt vmcnt(4)
	v_pk_mul_f32 v[142:143], v[28:29], v[222:223] op_sel:[1,0] op_sel_hi:[0,0]
	v_pk_fma_f32 v[28:29], v[28:29], v[218:219], v[142:143] op_sel:[0,0,0] op_sel_hi:[1,0,1] neg_lo:[0,0,1]
	v_pk_mul_f32 v[142:143], v[30:31], v[222:223] op_sel:[1,1] op_sel_hi:[0,1]
	v_pk_fma_f32 v[30:31], v[30:31], v[218:219], v[142:143] op_sel:[0,1,0] op_sel_hi:[1,1,1] neg_lo:[0,0,1]
	v_pk_mul_f32 v[142:143], v[24:25], v[224:225] op_sel:[1,0] op_sel_hi:[0,0]
	v_pk_fma_f32 v[24:25], v[24:25], v[220:221], v[142:143] op_sel:[0,0,0] op_sel_hi:[1,0,1] neg_lo:[0,0,1]
	v_pk_mul_f32 v[142:143], v[26:27], v[224:225] op_sel:[1,1] op_sel_hi:[0,1]
	v_pk_fma_f32 v[26:27], v[26:27], v[220:221], v[142:143] op_sel:[0,1,0] op_sel_hi:[1,1,1] neg_lo:[0,0,1]
	v_cvt_pk_bf16_f32 v146, v28, v29
	v_cvt_pk_bf16_f32 v147, v30, v31
	v_cvt_pk_bf16_f32 v148, v24, v25
	v_cvt_pk_bf16_f32 v149, v26, v27
	global_store_dwordx4 v130, v[146:149], s[6:7] sc1
	v_pk_mul_f32 v[142:143], v[20:21], v[222:223] op_sel:[1,0] op_sel_hi:[0,0]
	v_pk_fma_f32 v[20:21], v[20:21], v[218:219], v[142:143] op_sel:[0,0,0] op_sel_hi:[1,0,1] neg_lo:[0,0,1]
	v_pk_mul_f32 v[142:143], v[22:23], v[222:223] op_sel:[1,1] op_sel_hi:[0,1]
	v_pk_fma_f32 v[22:23], v[22:23], v[218:219], v[142:143] op_sel:[0,1,0] op_sel_hi:[1,1,1] neg_lo:[0,0,1]
	v_pk_mul_f32 v[142:143], v[16:17], v[224:225] op_sel:[1,0] op_sel_hi:[0,0]
	v_pk_fma_f32 v[16:17], v[16:17], v[220:221], v[142:143] op_sel:[0,0,0] op_sel_hi:[1,0,1] neg_lo:[0,0,1]
	v_pk_mul_f32 v[142:143], v[18:19], v[224:225] op_sel:[1,1] op_sel_hi:[0,1]
	v_pk_fma_f32 v[18:19], v[18:19], v[220:221], v[142:143] op_sel:[0,1,0] op_sel_hi:[1,1,1] neg_lo:[0,0,1]
	v_cvt_pk_bf16_f32 v150, v20, v21
	v_cvt_pk_bf16_f32 v151, v22, v23
	v_cvt_pk_bf16_f32 v152, v16, v17
	v_cvt_pk_bf16_f32 v153, v18, v19
	global_store_dwordx4 v130, v[150:153], s[6:7] offset:256 sc1
	s_add_u32 s6, s6, s33
	s_addc_u32 s7, s7, 0
	v_pk_mul_f32 v[12:13], v[12:13], v[140:141] op_sel:[0,1] op_sel_hi:[1,1]
	v_pk_mul_f32 v[14:15], v[14:15], v[140:141] op_sel:[0,1] op_sel_hi:[1,1]
	v_pk_mul_f32 v[4:5], v[4:5], v[140:141] op_sel:[0,1] op_sel_hi:[1,1]
	v_pk_mul_f32 v[6:7], v[6:7], v[140:141] op_sel:[0,1] op_sel_hi:[1,1]
	v_pk_mul_f32 v[8:9], v[8:9], v[140:141] op_sel:[0,1] op_sel_hi:[1,1]
	v_pk_mul_f32 v[10:11], v[10:11], v[140:141] op_sel:[0,1] op_sel_hi:[1,1]
	v_pk_mul_f32 v[0:1], v[0:1], v[140:141] op_sel:[0,1] op_sel_hi:[1,1]
	v_pk_mul_f32 v[2:3], v[2:3], v[140:141] op_sel:[0,1] op_sel_hi:[1,1]
	s_waitcnt vmcnt(2)
	v_pk_mul_f32 v[142:143], v[12:13], v[230:231] op_sel:[1,0] op_sel_hi:[0,0]
	v_pk_fma_f32 v[12:13], v[12:13], v[226:227], v[142:143] op_sel:[0,0,0] op_sel_hi:[1,0,1] neg_lo:[0,0,1]
	v_pk_mul_f32 v[142:143], v[14:15], v[230:231] op_sel:[1,1] op_sel_hi:[0,1]
	v_pk_fma_f32 v[14:15], v[14:15], v[226:227], v[142:143] op_sel:[0,1,0] op_sel_hi:[1,1,1] neg_lo:[0,0,1]
	v_pk_mul_f32 v[142:143], v[4:5], v[232:233] op_sel:[1,0] op_sel_hi:[0,0]
	v_pk_fma_f32 v[4:5], v[4:5], v[228:229], v[142:143] op_sel:[0,0,0] op_sel_hi:[1,0,1] neg_lo:[0,0,1]
	v_pk_mul_f32 v[142:143], v[6:7], v[232:233] op_sel:[1,1] op_sel_hi:[0,1]
	v_pk_fma_f32 v[6:7], v[6:7], v[228:229], v[142:143] op_sel:[0,1,0] op_sel_hi:[1,1,1] neg_lo:[0,0,1]
	v_cvt_pk_bf16_f32 v146, v12, v13
	v_cvt_pk_bf16_f32 v147, v14, v15
	v_cvt_pk_bf16_f32 v148, v4, v5
	v_cvt_pk_bf16_f32 v149, v6, v7
	global_store_dwordx4 v130, v[146:149], s[6:7] sc1
	v_pk_mul_f32 v[142:143], v[8:9], v[230:231] op_sel:[1,0] op_sel_hi:[0,0]
	v_pk_fma_f32 v[8:9], v[8:9], v[226:227], v[142:143] op_sel:[0,0,0] op_sel_hi:[1,0,1] neg_lo:[0,0,1]
	v_pk_mul_f32 v[142:143], v[10:11], v[230:231] op_sel:[1,1] op_sel_hi:[0,1]
	v_pk_fma_f32 v[10:11], v[10:11], v[226:227], v[142:143] op_sel:[0,1,0] op_sel_hi:[1,1,1] neg_lo:[0,0,1]
	v_pk_mul_f32 v[142:143], v[0:1], v[232:233] op_sel:[1,0] op_sel_hi:[0,0]
	v_pk_fma_f32 v[0:1], v[0:1], v[228:229], v[142:143] op_sel:[0,0,0] op_sel_hi:[1,0,1] neg_lo:[0,0,1]
	v_pk_mul_f32 v[142:143], v[2:3], v[232:233] op_sel:[1,1] op_sel_hi:[0,1]
	v_pk_fma_f32 v[2:3], v[2:3], v[228:229], v[142:143] op_sel:[0,1,0] op_sel_hi:[1,1,1] neg_lo:[0,0,1]
	v_cvt_pk_bf16_f32 v150, v8, v9
	v_cvt_pk_bf16_f32 v151, v10, v11
	v_cvt_pk_bf16_f32 v152, v0, v1
	v_cvt_pk_bf16_f32 v153, v2, v3
	global_store_dwordx4 v130, v[150:153], s[6:7] offset:256 sc1
	s_branch .LBB0_971
.Lq1_plain:
	v_pk_mul_f32 v[126:127], v[126:127], v[134:135] op_sel_hi:[1,0]
	v_pk_mul_f32 v[128:129], v[128:129], v[134:135] op_sel_hi:[1,0]
	v_pk_mul_f32 v[122:123], v[122:123], v[134:135] op_sel_hi:[1,0]
	v_pk_mul_f32 v[124:125], v[124:125], v[134:135] op_sel_hi:[1,0]
	v_pk_mul_f32 v[118:119], v[118:119], v[134:135] op_sel_hi:[1,0]
	v_pk_mul_f32 v[120:121], v[120:121], v[134:135] op_sel_hi:[1,0]
	v_pk_mul_f32 v[114:115], v[114:115], v[134:135] op_sel_hi:[1,0]
	v_pk_mul_f32 v[116:117], v[116:117], v[134:135] op_sel_hi:[1,0]
	v_cvt_pk_bf16_f32 v146, v126, v127
	v_cvt_pk_bf16_f32 v147, v128, v129
	v_cvt_pk_bf16_f32 v148, v122, v123
	v_cvt_pk_bf16_f32 v149, v124, v125
	global_store_dwordx4 v130, v[146:149], s[6:7] sc1
	v_cvt_pk_bf16_f32 v150, v118, v119
	v_cvt_pk_bf16_f32 v151, v120, v121
	v_cvt_pk_bf16_f32 v152, v114, v115
	v_cvt_pk_bf16_f32 v153, v116, v117
	global_store_dwordx4 v130, v[150:153], s[6:7] offset:256 sc1
	s_add_u32 s6, s6, s33
	s_addc_u32 s7, s7, 0
	v_pk_mul_f32 v[108:109], v[108:109], v[134:135] op_sel:[0,1] op_sel_hi:[1,1]
	v_pk_mul_f32 v[110:111], v[110:111], v[134:135] op_sel:[0,1] op_sel_hi:[1,1]
	v_pk_mul_f32 v[104:105], v[104:105], v[134:135] op_sel:[0,1] op_sel_hi:[1,1]
	v_pk_mul_f32 v[106:107], v[106:107], v[134:135] op_sel:[0,1] op_sel_hi:[1,1]
	v_pk_mul_f32 v[100:101], v[100:101], v[134:135] op_sel:[0,1] op_sel_hi:[1,1]
	v_pk_mul_f32 v[102:103], v[102:103], v[134:135] op_sel:[0,1] op_sel_hi:[1,1]
	v_pk_mul_f32 v[96:97], v[96:97], v[134:135] op_sel:[0,1] op_sel_hi:[1,1]
	v_pk_mul_f32 v[98:99], v[98:99], v[134:135] op_sel:[0,1] op_sel_hi:[1,1]
	v_cvt_pk_bf16_f32 v146, v108, v109
	v_cvt_pk_bf16_f32 v147, v110, v111
	v_cvt_pk_bf16_f32 v148, v104, v105
	v_cvt_pk_bf16_f32 v149, v106, v107
	global_store_dwordx4 v130, v[146:149], s[6:7] sc1
	v_cvt_pk_bf16_f32 v150, v100, v101
	v_cvt_pk_bf16_f32 v151, v102, v103
	v_cvt_pk_bf16_f32 v152, v96, v97
	v_cvt_pk_bf16_f32 v153, v98, v99
	global_store_dwordx4 v130, v[150:153], s[6:7] offset:256 sc1
	s_add_u32 s6, s6, s33
	s_addc_u32 s7, s7, 0
	v_pk_mul_f32 v[92:93], v[92:93], v[136:137] op_sel_hi:[1,0]
	v_pk_mul_f32 v[94:95], v[94:95], v[136:137] op_sel_hi:[1,0]
	v_pk_mul_f32 v[88:89], v[88:89], v[136:137] op_sel_hi:[1,0]
	v_pk_mul_f32 v[90:91], v[90:91], v[136:137] op_sel_hi:[1,0]
	v_pk_mul_f32 v[84:85], v[84:85], v[136:137] op_sel_hi:[1,0]
	v_pk_mul_f32 v[86:87], v[86:87], v[136:137] op_sel_hi:[1,0]
	v_pk_mul_f32 v[80:81], v[80:81], v[136:137] op_sel_hi:[1,0]
	v_pk_mul_f32 v[82:83], v[82:83], v[136:137] op_sel_hi:[1,0]
	v_cvt_pk_bf16_f32 v146, v92, v93
	v_cvt_pk_bf16_f32 v147, v94, v95
	v_cvt_pk_bf16_f32 v148, v88, v89
	v_cvt_pk_bf16_f32 v149, v90, v91
	global_store_dwordx4 v130, v[146:149], s[6:7] sc1
	v_cvt_pk_bf16_f32 v150, v84, v85
	v_cvt_pk_bf16_f32 v151, v86, v87
	v_cvt_pk_bf16_f32 v152, v80, v81
	v_cvt_pk_bf16_f32 v153, v82, v83
	global_store_dwordx4 v130, v[150:153], s[6:7] offset:256 sc1
	s_add_u32 s6, s6, s33
	s_addc_u32 s7, s7, 0
	v_pk_mul_f32 v[76:77], v[76:77], v[136:137] op_sel:[0,1] op_sel_hi:[1,1]
	v_pk_mul_f32 v[78:79], v[78:79], v[136:137] op_sel:[0,1] op_sel_hi:[1,1]
	v_pk_mul_f32 v[72:73], v[72:73], v[136:137] op_sel:[0,1] op_sel_hi:[1,1]
	v_pk_mul_f32 v[74:75], v[74:75], v[136:137] op_sel:[0,1] op_sel_hi:[1,1]
	v_pk_mul_f32 v[68:69], v[68:69], v[136:137] op_sel:[0,1] op_sel_hi:[1,1]
	v_pk_mul_f32 v[70:71], v[70:71], v[136:137] op_sel:[0,1] op_sel_hi:[1,1]
	v_pk_mul_f32 v[64:65], v[64:65], v[136:137] op_sel:[0,1] op_sel_hi:[1,1]
	v_pk_mul_f32 v[66:67], v[66:67], v[136:137] op_sel:[0,1] op_sel_hi:[1,1]
	v_cvt_pk_bf16_f32 v146, v76, v77
	v_cvt_pk_bf16_f32 v147, v78, v79
	v_cvt_pk_bf16_f32 v148, v72, v73
	v_cvt_pk_bf16_f32 v149, v74, v75
	global_store_dwordx4 v130, v[146:149], s[6:7] sc1
	v_cvt_pk_bf16_f32 v150, v68, v69
	v_cvt_pk_bf16_f32 v151, v70, v71
	v_cvt_pk_bf16_f32 v152, v64, v65
	v_cvt_pk_bf16_f32 v153, v66, v67
	global_store_dwordx4 v130, v[150:153], s[6:7] offset:256 sc1
	s_add_u32 s6, s6, s34
	s_addc_u32 s7, s7, 0
	v_pk_mul_f32 v[60:61], v[60:61], v[138:139] op_sel_hi:[1,0]
	v_pk_mul_f32 v[62:63], v[62:63], v[138:139] op_sel_hi:[1,0]
	v_pk_mul_f32 v[56:57], v[56:57], v[138:139] op_sel_hi:[1,0]
	v_pk_mul_f32 v[58:59], v[58:59], v[138:139] op_sel_hi:[1,0]
	v_pk_mul_f32 v[52:53], v[52:53], v[138:139] op_sel_hi:[1,0]
	v_pk_mul_f32 v[54:55], v[54:55], v[138:139] op_sel_hi:[1,0]
	v_pk_mul_f32 v[48:49], v[48:49], v[138:139] op_sel_hi:[1,0]
	v_pk_mul_f32 v[50:51], v[50:51], v[138:139] op_sel_hi:[1,0]
	v_cvt_pk_bf16_f32 v146, v60, v61
	v_cvt_pk_bf16_f32 v147, v62, v63
	v_cvt_pk_bf16_f32 v148, v56, v57
	v_cvt_pk_bf16_f32 v149, v58, v59
	global_store_dwordx4 v130, v[146:149], s[6:7] sc1
	v_cvt_pk_bf16_f32 v150, v52, v53
	v_cvt_pk_bf16_f32 v151, v54, v55
	v_cvt_pk_bf16_f32 v152, v48, v49
	v_cvt_pk_bf16_f32 v153, v50, v51
	global_store_dwordx4 v130, v[150:153], s[6:7] offset:256 sc1
	s_add_u32 s6, s6, s33
	s_addc_u32 s7, s7, 0
	v_pk_mul_f32 v[44:45], v[44:45], v[138:139] op_sel:[0,1] op_sel_hi:[1,1]
	v_pk_mul_f32 v[46:47], v[46:47], v[138:139] op_sel:[0,1] op_sel_hi:[1,1]
	v_pk_mul_f32 v[40:41], v[40:41], v[138:139] op_sel:[0,1] op_sel_hi:[1,1]
	v_pk_mul_f32 v[42:43], v[42:43], v[138:139] op_sel:[0,1] op_sel_hi:[1,1]
	v_pk_mul_f32 v[36:37], v[36:37], v[138:139] op_sel:[0,1] op_sel_hi:[1,1]
	v_pk_mul_f32 v[38:39], v[38:39], v[138:139] op_sel:[0,1] op_sel_hi:[1,1]
	v_pk_mul_f32 v[32:33], v[32:33], v[138:139] op_sel:[0,1] op_sel_hi:[1,1]
	v_pk_mul_f32 v[34:35], v[34:35], v[138:139] op_sel:[0,1] op_sel_hi:[1,1]
	v_cvt_pk_bf16_f32 v146, v44, v45
	v_cvt_pk_bf16_f32 v147, v46, v47
	v_cvt_pk_bf16_f32 v148, v40, v41
	v_cvt_pk_bf16_f32 v149, v42, v43
	global_store_dwordx4 v130, v[146:149], s[6:7] sc1
	v_cvt_pk_bf16_f32 v150, v36, v37
	v_cvt_pk_bf16_f32 v151, v38, v39
	v_cvt_pk_bf16_f32 v152, v32, v33
	v_cvt_pk_bf16_f32 v153, v34, v35
	global_store_dwordx4 v130, v[150:153], s[6:7] offset:256 sc1
	s_add_u32 s6, s6, s33
	s_addc_u32 s7, s7, 0
	v_pk_mul_f32 v[28:29], v[28:29], v[140:141] op_sel_hi:[1,0]
	v_pk_mul_f32 v[30:31], v[30:31], v[140:141] op_sel_hi:[1,0]
	v_pk_mul_f32 v[24:25], v[24:25], v[140:141] op_sel_hi:[1,0]
	v_pk_mul_f32 v[26:27], v[26:27], v[140:141] op_sel_hi:[1,0]
	v_pk_mul_f32 v[20:21], v[20:21], v[140:141] op_sel_hi:[1,0]
	v_pk_mul_f32 v[22:23], v[22:23], v[140:141] op_sel_hi:[1,0]
	v_pk_mul_f32 v[16:17], v[16:17], v[140:141] op_sel_hi:[1,0]
	v_pk_mul_f32 v[18:19], v[18:19], v[140:141] op_sel_hi:[1,0]
	v_cvt_pk_bf16_f32 v146, v28, v29
	v_cvt_pk_bf16_f32 v147, v30, v31
	v_cvt_pk_bf16_f32 v148, v24, v25
	v_cvt_pk_bf16_f32 v149, v26, v27
	global_store_dwordx4 v130, v[146:149], s[6:7] sc1
	v_cvt_pk_bf16_f32 v150, v20, v21
	v_cvt_pk_bf16_f32 v151, v22, v23
	v_cvt_pk_bf16_f32 v152, v16, v17
	v_cvt_pk_bf16_f32 v153, v18, v19
	global_store_dwordx4 v130, v[150:153], s[6:7] offset:256 sc1
	s_add_u32 s6, s6, s33
	s_addc_u32 s7, s7, 0
	v_pk_mul_f32 v[12:13], v[12:13], v[140:141] op_sel:[0,1] op_sel_hi:[1,1]
	v_pk_mul_f32 v[14:15], v[14:15], v[140:141] op_sel:[0,1] op_sel_hi:[1,1]
	v_pk_mul_f32 v[4:5], v[4:5], v[140:141] op_sel:[0,1] op_sel_hi:[1,1]
	v_pk_mul_f32 v[6:7], v[6:7], v[140:141] op_sel:[0,1] op_sel_hi:[1,1]
	v_pk_mul_f32 v[8:9], v[8:9], v[140:141] op_sel:[0,1] op_sel_hi:[1,1]
	v_pk_mul_f32 v[10:11], v[10:11], v[140:141] op_sel:[0,1] op_sel_hi:[1,1]
	v_pk_mul_f32 v[0:1], v[0:1], v[140:141] op_sel:[0,1] op_sel_hi:[1,1]
	v_pk_mul_f32 v[2:3], v[2:3], v[140:141] op_sel:[0,1] op_sel_hi:[1,1]
	v_cvt_pk_bf16_f32 v146, v12, v13
	v_cvt_pk_bf16_f32 v147, v14, v15
	v_cvt_pk_bf16_f32 v148, v4, v5
	v_cvt_pk_bf16_f32 v149, v6, v7
	global_store_dwordx4 v130, v[146:149], s[6:7] sc1
	v_cvt_pk_bf16_f32 v150, v8, v9
	v_cvt_pk_bf16_f32 v151, v10, v11
	v_cvt_pk_bf16_f32 v152, v0, v1
	v_cvt_pk_bf16_f32 v153, v2, v3
	global_store_dwordx4 v130, v[150:153], s[6:7] offset:256 sc1
	s_branch .LBB0_971
